# per-XCD queues now guarded by the barrier census (falls back to the single queue), sample-step radix loop trimmed
# speedup vs baseline: 1.0385x; 1.0032x over previous
; __device__ __forceinline__ void select_blocks(const LAS float* sc, LAS unsigned* selm, int jhi, int f1, int f2, int lane) {
;     ...
;     unsigned prefix = 0u;
; #pragma unroll 1
;     ...
;         const unsigned c = prefix | (1u << bit); int cnt = 0;
; #pragma unroll
;         for (int rr = 0; rr < 4; ++rr) cnt += __popcll(__ballot(cand[rr] && key[rr] >= c));
;         if (cnt >= 13) prefix = c;
;     }
;     int cgt = 0; unsigned long long be[4];
; #pragma unroll
;     for (int rr = 0; rr < 4; ++rr) { cgt += __popcll(__ballot(cand[rr] && key[rr] > prefix)); be[rr] = __ballot(cand[rr] && key[rr] == prefix); }
;     const int need = 13 - cgt; const unsigned long long lt = (1ull << lane) - 1ull;
;     int before = 0;
; #pragma unroll
;     for (int rr = 0; rr < 4; ++rr) before += __popcll(be[rr] & lt);
.LBB0_896:
	s_lshl_b32 s20, 1, s26
	s_or_b32 s27, s20, s0
	s_waitcnt lgkmcnt(0)
	v_cmp_le_u32_e64 s[20:21], s27, v0
	v_cmp_le_u32_e32 vcc, s27, v3
	v_cmp_le_u32_e64 s[22:23], s27, v12
	v_cmp_le_u32_e64 s[24:25], s27, v2
	s_bcnt1_i32_b64 s28, vcc
	s_bcnt1_i32_b64 s20, s[20:21]
	s_bcnt1_i32_b64 s21, s[22:23]
	s_add_i32 s20, s20, s28
	s_bcnt1_i32_b64 s22, s[24:25]
	s_add_i32 s20, s20, s21
	s_add_i32 s20, s20, s22
	s_cmp_gt_u32 s20, 12
	s_cselect_b32 s0, s27, s0
	s_add_i32 s26, s26, -1
	s_cmp_eq_u32 s26, -1
	s_cbranch_scc0 .LBB0_896
	v_cmp_lt_u32_e32 vcc, s0, v3
	s_and_b64 s[20:21], s[8:9], vcc
	v_cndmask_b32_e64 v13, 0, 1, s[20:21]
	s_xor_b64 s[84:85], s[20:21], -1
	v_cmp_lt_u32_e64 s[20:21], s0, v0
	s_and_b64 s[26:27], s[10:11], s[20:21]
	v_cmp_ne_u32_e32 vcc, 0, v13
	v_cndmask_b32_e64 v13, 0, 1, s[26:27]
	v_cmp_lt_u32_e64 s[22:23], s0, v12
	v_cmp_ne_u32_e64 s[20:21], 0, v13
	s_and_b64 s[28:29], s[54:55], s[22:23]
	s_bcnt1_i32_b64 s48, s[20:21]
	v_cmp_eq_u32_e64 s[20:21], s0, v0
	v_cndmask_b32_e64 v0, 0, 1, s[28:29]
	v_cmp_lt_u32_e64 s[24:25], s0, v2
	v_cmp_ne_u32_e64 s[22:23], 0, v0
	s_and_b64 s[72:73], s[56:57], s[24:25]
	s_bcnt1_i32_b64 s41, vcc
	v_cmp_eq_u32_e32 vcc, s0, v3
	s_bcnt1_i32_b64 s71, s[22:23]
	v_cmp_eq_u32_e64 s[22:23], s0, v12
	v_cndmask_b32_e64 v12, 0, 1, s[72:73]
	s_and_b64 s[74:75], s[8:9], vcc
	v_cmp_ne_u32_e64 s[24:25], 0, v12
	v_cndmask_b32_e64 v3, 0, 1, s[74:75]
	s_and_b64 s[30:31], s[10:11], s[20:21]
	s_bcnt1_i32_b64 s91, s[24:25]
	v_cmp_eq_u32_e64 s[24:25], s0, v2
	v_cmp_ne_u32_e32 vcc, 0, v3
	v_cndmask_b32_e64 v13, 0, 1, s[30:31]
	s_and_b64 s[36:37], s[56:57], s[24:25]
	v_cmp_ne_u32_e64 s[20:21], 0, v13
	s_and_b64 s[34:35], s[54:55], s[22:23]
	v_cndmask_b32_e64 v2, 0, 1, s[36:37]
	v_and_b32_e32 v12, vcc_lo, v90
	v_cndmask_b32_e64 v0, 0, 1, s[34:35]
	v_cmp_ne_u32_e64 s[24:25], 0, v2
	v_and_b32_e32 v2, vcc_hi, v81
	v_bcnt_u32_b32 v12, v12, 0
	v_and_b32_e32 v14, s20, v90
	v_cmp_ne_u32_e64 s[22:23], 0, v0
	v_bcnt_u32_b32 v2, v2, v12
	v_and_b32_e32 v12, s21, v81
	v_bcnt_u32_b32 v14, v14, 0
	v_bcnt_u32_b32 v12, v12, v14
	v_and_b32_e32 v14, s22, v90
	v_add_u32_e32 v2, v12, v2
	v_and_b32_e32 v12, s23, v81
	v_bcnt_u32_b32 v14, v14, 0
	v_and_b32_e32 v15, s24, v90
	s_add_i32 s0, s41, s48
	v_bcnt_u32_b32 v12, v12, v14
	v_and_b32_e32 v14, s25, v81
	v_bcnt_u32_b32 v15, v15, 0
	s_add_i32 s0, s0, s71
	v_bcnt_u32_b32 v14, v14, v15
	s_add_i32 s0, s0, s91
	v_add3_u32 v12, v2, v12, v14
	s_sub_i32 s0, 13, s0
	v_mov_b32_e32 v2, 1
	s_and_saveexec_b64 s[20:21], s[84:85]
	s_cbranch_execz .LBB0_903
	s_xor_b64 s[24:25], s[74:75], -1
	s_mov_b64 s[22:23], 0
	s_and_saveexec_b64 s[74:75], s[24:25]
	s_xor_b64 s[24:25], exec, s[74:75]
	s_cbranch_execz .LBB0_931
	s_and_b64 s[22:23], s[52:53], exec
	s_andn2_saveexec_b64 s[24:25], s[24:25]
	s_cbranch_execnz .LBB0_932

; __device__ __forceinline__ unsigned xb_add(unsigned* p, unsigned v) { return __hip_atomic_fetch_add(p, v, __ATOMIC_RELAXED, __HIP_MEMORY_SCOPE_AGENT); }
; __device__ __forceinline__ void xcd_barrier(const XcdBarrier& b) {
;     ...
;         unsigned nloc = b.st[0], nx = b.st[1];
;         if (nloc == 0u) { xcd_barrier_complete(bar, b.x, nloc, nx); b.st[0] = nloc; b.st[1] = nx; }
; __global__ void __launch_bounds__(NWAVES * 64, 2) hybrid_fwd(Args args) {
;     ...
;         for (;;) {
;             if (C.tid == 0) MISC[16] = xb_add(ctl + 320, 1u);
;             __syncthreads();
;             const unsigned qi = MISC[16];
;             __syncthreads();
.LBB0_1113:
	s_and_saveexec_b64 s[16:17], s[4:5]
	s_cbranch_execz .LBB0_1115
	s_waitcnt vmcnt(0)
	v_mov_b32_e32 v2, 0x23020
	ds_read2_b32 v[2:3], v2 offset1:1
	s_waitcnt lgkmcnt(0)
	v_readfirstlane_b32 s98, v2
	v_readfirstlane_b32 s99, v3
	s_cmp_eq_u32 s98, 32
	s_cselect_b32 s98, 1, 0
	s_cmp_eq_u32 s99, 8
	s_cselect_b32 s99, 1, 0
	s_and_b32 s100, s98, s99
	s_cmp_eq_u32 s100, 0
	s_cbranch_scc1 .Lnsaq_single
	v_readlane_b32 s101, v255, 6
	s_and_b32 s101, s101, 7
	s_lshl_b32 s98, s101, 8
	s_add_i32 s98, s98, 0x800
	s_mov_b32 s99, 0
	v_lshl_add_u64 v[2:3], v[194:195], 0, s[98:99]
	global_atomic_add v0, v[2:3], v228, off sc0
	v_mov_b32_e32 v2, s89
	s_waitcnt vmcnt(0) lgkmcnt(0)
	v_lshlrev_b32_e32 v0, 3, v0
	v_or_b32_e32 v0, s101, v0
	s_branch .Lnsaq_done
.Lnsaq_single:
	global_atomic_add v0, v[194:195], v228, off offset:1280 sc0
	v_mov_b32_e32 v2, s89
	s_waitcnt vmcnt(0) lgkmcnt(0)
.Lnsaq_done:
	ds_write_b32 v2, v0
